# GLA scan: k^T and v operands via ds_read_b64_tr_b16 from row tiles (no 2-byte gathers), 2-chunk-deep prefetch
# speedup vs baseline: 1.0251x; 1.0085x over previous
; __device__ __forceinline__ void gla_scan_phase(const Params& p, int j, bool need_ctx, char* smem, int tid, int bid) {
;     ...
;     const u16* QB = (const u16*)(p.ws + OFF_GQB);
;     const u16* KB2 = (const u16*)((const char*)p.out + OUT_GKB);
;     const float* EBE = (const float*)((const char*)p.out + OUT_EBE);
;     const u16* qsrc = dir ? QB + h * 128 : P + h * 128;
;     const u16* ksrc = dir ? KB2 + h * 128 : P + 512 + h * 128;
;     const long rst = dir ? 512 : LDP;
;     const long sgn = dir ? -1 : 1;
.Lgs_map_done:
	v_readlane_b32 s0, v253, 28
	v_readlane_b32 s1, v253, 29
	v_readlane_b32 s4, v253, 43
	v_readlane_b32 s5, v253, 44
	v_readlane_b32 s8, v253, 45
	v_readlane_b32 s9, v253, 46
	v_readlane_b32 s10, v253, 47
	v_readlane_b32 s11, v253, 48
	v_readlane_b32 s18, v253, 41
	v_readlane_b32 s19, v253, 42
	s_movk_i32 s16, 0x400
	s_cmp_eq_u32 s55, 0
	s_cselect_b32 s34, 0x1840, s16
	s_cselect_b32 s80, 0, 63
	s_cselect_b32 s22, s92, s0
	s_cselect_b32 s23, s93, s1
	s_cselect_b32 s24, s4, s8
	s_cselect_b32 s25, s5, s9
	s_cselect_b32 s30, s12, s18
	s_cselect_b32 s31, s13, s19
	s_lshl_b32 s16, s73, 8
	s_add_u32 s22, s22, s16
	s_addc_u32 s23, s23, 0
	s_add_u32 s24, s24, s16
	s_addc_u32 s25, s25, 0
	s_lshl_b32 s0, s73, 9
	s_lshl_b32 s1, s72, 7
	s_add_u32 s0, s0, s1
	s_add_u32 s30, s30, s0
	s_addc_u32 s31, s31, 0
	s_add_u32 s0, s0, 0x800
	s_add_u32 s26, s92, s0
	s_addc_u32 s27, s93, 0
	s_mul_i32 s4, s55, 0x110000
	s_lshl_b32 s5, s73, 9
	s_add_u32 s4, s4, s5
	s_add_u32 s28, s10, s4
	s_addc_u32 s29, s11, 0
	v_and_b32_e32 v100, 63, v203
	v_lshrrev_b32_e32 v101, 6, v203
	v_and_b32_e32 v102, 31, v203
	v_bfe_u32 v103, v203, 5, 1
	v_and_b32_e32 v104, 15, v203
	v_bfe_u32 v105, v203, 1, 3
	v_readfirstlane_b32 s0, v101
	s_mov_b32 s81, s0
	s_lshr_b32 s1, s0, 1
	s_and_b32 s77, s1, 1
	s_and_b32 s4, s0, 1
	s_cmp_gt_u32 s0, 3
	s_cselect_b32 s76, 2, 0
	s_cmp_eq_u32 s0, 1
	s_cselect_b32 s76, 1, s76
	s_lshl_b32 s5, s4, 13
	s_lshl_b32 s8, s77, 13
	s_add_u32 s9, s5, 0x4000
	s_add_u32 s10, s5, 0x12000
	s_cmp_eq_u32 s76, 2
	s_cselect_b32 s72, s8, s9
	s_cselect_b32 s73, s10, s8
	v_xor_b32_e32 v107, v103, v104
	v_lshlrev_b32_e32 v107, 4, v107
	v_lshl_or_b32 v107, v102, 8, v107
	v_add_u32_e32 v108, s72, v107
	v_add_u32_e32 v109, s73, v107
	v_mov_b32_e32 v220, v108
	v_mov_b32_e32 v228, v109
	v_xor_b32_e32 v107, v103, v105
	v_lshlrev_b32_e32 v107, 4, v107
	v_lshl_or_b32 v107, v102, 7, v107
	s_lshl_b32 s9, s77, 12
	s_add_u32 s9, s9, 0x10000
	v_add_u32_e32 v249, s9, v107
	s_lshl_b32 s8, s4, 2
	v_xor_b32_e32 v108, s8, v105
	v_lshlrev_b32_e32 v108, 4, v108
	v_lshl_or_b32 v108, v102, 7, v108
	v_lshl_or_b32 v108, v103, 3, v108
	v_add_u32_e32 v108, s9, v108
	s_cmp_eq_u32 s76, 2
	s_cbranch_scc1 .Lgs_sclw_done
	v_mov_b32_e32 v249, v108
.Lgs_sclw_done:
	s_lshl_b32 s8, s1, 2
	v_xor_b32_e32 v108, s8, v104
	v_lshlrev_b32_e32 v108, 4, v108
	v_lshl_or_b32 v108, v102, 8, v108
	v_lshl_or_b32 v108, v103, 3, v108
	s_add_u32 s9, s5, 0x12000
	v_add_u32_e32 v250, s9, v108
	s_lshl_b32 s9, s1, 7
	s_add_u32 s9, s9, 0x16000
	v_lshlrev_b32_e32 v108, 4, v103
	v_add_u32_e32 v252, s9, v108
	v_lshrrev_b32_e32 v106, 3, v203
	v_and_b32_e32 v107, 7, v203
	v_and_b32_e32 v108, 15, v106
	v_xor_b32_e32 v108, v107, v108
	v_lshlrev_b32_e32 v108, 4, v108
	v_lshl_or_b32 v192, v106, 8, v108
	v_xor_b32_e32 v193, 0x80, v192
	v_lshlrev_b32_e32 v198, 4, v107
	v_lshl_or_b32 v196, v106, 7, v198
	v_add_u32_e32 v196, 0xc000, v196
	v_bfe_u32 v108, v203, 4, 1
	v_bfe_u32 v109, v203, 2, 2
	v_and_b32_e32 v198, 3, v203
	v_lshrrev_b32_e32 v199, 1, v198
	v_lshl_or_b32 v199, v108, 1, v199
	v_and_b32_e32 v198, 1, v198
	v_lshlrev_b32_e32 v198, 3, v198
	v_lshl_or_b32 v109, v103, 3, v109
	s_lshl_b32 s9, s1, 2
	v_or_b32_e32 v200, s9, v199
	v_add_u32_e32 v153, 0, v109
	v_xor_b32_e32 v140, v200, v153
	v_lshlrev_b32_e32 v140, 4, v140
	v_lshl_or_b32 v140, v153, 8, v140
	v_or_b32_e32 v140, v140, v198
	v_add_u32_e32 v153, 4, v109
	v_xor_b32_e32 v141, v200, v153
	v_lshlrev_b32_e32 v141, 4, v141
	v_lshl_or_b32 v141, v153, 8, v141
	v_or_b32_e32 v141, v141, v198
	s_lshl_b32 s9, s4, 2
	v_or_b32_e32 v200, s9, v199
	v_lshlrev_b32_e32 v142, 4, v200
	v_lshl_or_b32 v142, v109, 7, v142
	v_or_b32_e32 v142, v142, v198
	v_lshlrev_b32_e32 v191, 2, v203
	v_add_u32_e32 v197, 0x16000, v191
	v_xor_b32_e32 v198, s80, v106
	v_mul_lo_u32 v198, v198, s34
	v_lshl_add_u32 v166, v107, 4, v198
	s_movk_i32 s9, 0x1840
	v_xor_b32_e32 v198, s80, v106
	v_mul_lo_u32 v198, v198, s9
	v_lshl_add_u32 v183, v107, 4, v198
	s_cmp_eq_u32 s76, 2
	s_cbranch_scc0 .Lgs_masks
	s_lshl_b32 s9, s77, 5
	v_lshl_add_u32 v109, v103, 2, s9
	s_lshl_b32 s9, s4, 6
	v_lshl_add_u32 v108, v102, 1, s9
	v_add_u32_e32 v198, 0, v109
	v_xor_b32_e32 v198, s80, v198
	v_lshl_add_u32 v204, v198, 11, v108
	v_add_u32_e32 v198, 1, v109
	v_xor_b32_e32 v198, s80, v198
	v_lshl_add_u32 v205, v198, 11, v108
	v_add_u32_e32 v198, 2, v109
	v_xor_b32_e32 v198, s80, v198
	v_lshl_add_u32 v206, v198, 11, v108
	v_add_u32_e32 v198, 3, v109
	v_xor_b32_e32 v198, s80, v198
	v_lshl_add_u32 v207, v198, 11, v108
	v_add_u32_e32 v198, 8, v109
	v_xor_b32_e32 v198, s80, v198
	v_lshl_add_u32 v208, v198, 11, v108
	v_add_u32_e32 v198, 9, v109
	v_xor_b32_e32 v198, s80, v198
	v_lshl_add_u32 v209, v198, 11, v108
	v_add_u32_e32 v198, 10, v109
	v_xor_b32_e32 v198, s80, v198
	v_lshl_add_u32 v210, v198, 11, v108
	v_add_u32_e32 v198, 11, v109
	v_xor_b32_e32 v198, s80, v198
	v_lshl_add_u32 v211, v198, 11, v108
	v_add_u32_e32 v198, 16, v109
	v_xor_b32_e32 v198, s80, v198
	v_lshl_add_u32 v212, v198, 11, v108
	v_add_u32_e32 v198, 17, v109
	v_xor_b32_e32 v198, s80, v198
	v_lshl_add_u32 v213, v198, 11, v108
	v_add_u32_e32 v198, 18, v109
	v_xor_b32_e32 v198, s80, v198
	v_lshl_add_u32 v214, v198, 11, v108
	v_add_u32_e32 v198, 19, v109
	v_xor_b32_e32 v198, s80, v198
	v_lshl_add_u32 v215, v198, 11, v108
	v_add_u32_e32 v198, 24, v109
	v_xor_b32_e32 v198, s80, v198
	v_lshl_add_u32 v216, v198, 11, v108
	v_add_u32_e32 v198, 25, v109
	v_xor_b32_e32 v198, s80, v198
	v_lshl_add_u32 v217, v198, 11, v108
	v_add_u32_e32 v198, 26, v109
	v_xor_b32_e32 v198, s80, v198
	v_lshl_add_u32 v218, v198, 11, v108
	v_add_u32_e32 v198, 27, v109
	v_xor_b32_e32 v198, s80, v198
	v_lshl_add_u32 v219, v198, 11, v108
	s_branch .Lgs_roles_done

; __device__ __forceinline__ void gla_scan_phase(const Params& p, int j, bool need_ctx, char* smem, int tid, int bid) {
;     ...
;     GLA_PREFETCH(0);
;     for (int ci = 0; ci < 68; ++ci) {
;       asm volatile("" : "+v"(tid));
;       const int lane = tid & 63, wid = tid >> 6, l32 = lane & 31, hi = lane >> 5;
;       const int tbg = wid >> 2, kd = (wid & 3) * 32 + l32;
;       const int dvc = tid & 63, tg = tid >> 6;
;       const bool is_ctx = ci < 4; const int c = is_ctx ? ci : ci - 4; const int TT = is_ctx ? CTXL : SEQL;
;       const int base = is_ctx ? ML + b * CTXL : b * SEQL;
;       char* vT = vT0 + (ci & 1) * 40960;
;       {
;         if (tid < 128) ebend[tid] = ebv;
;         const int r = tid >> 3, c0 = tid & 7;
;         *(u32x4*)(qbL + swz256(r, c0)) = qx[0]; *(u32x4*)(qbL + swz256(r, c0 + 8)) = qx[1];
;         *(u32x4*)(kinvL + swz256(r, c0)) = kx[0]; *(u32x4*)(kinvL + swz256(r, c0 + 8)) = kx[1];
;         const int kdt = tid & 127, tgk = tid >> 7;
;         u32x4 w0 = {kt[0] | (kt[1] << 16), kt[2] | (kt[3] << 16), kt[4] | (kt[5] << 16), kt[6] | (kt[7] << 16)};
;         u32x4 w1 = {kt[8] | (kt[9] << 16), kt[10] | (kt[11] << 16), kt[12] | (kt[13] << 16), kt[14] | (kt[15] << 16)};
;         *(u32x4*)(kendT + swz128(kdt, tgk)) = w0;
;         *(u32x4*)(kendT + swz128(kdt, tgk + 4)) = w1;
;         u32x4 wv = {vv[0] | (vv[1] << 16), vv[2] | (vv[3] << 16), vv[4] | (vv[5] << 16), vv[6] | (vv[7] << 16)};
;         *(u32x4*)(vT + swz128(dvc, tg)) = wv;
;       }
;       __builtin_amdgcn_sched_barrier(0);
;       if (ci + 1 < 68) GLA_PREFETCH(ci + 1);
;       __builtin_amdgcn_sched_barrier(0);
;       __syncthreads();
;       f32x16 oacc;
; #pragma unroll
;       for (int r = 0; r < 16; ++r) oacc[r] = 0.f;
;       const int tbo = (wid - 4) >> 1, dvbo = (wid - 4) & 1;
;       const bool need_o = !is_ctx || need_ctx;
;       if (!need_o) {
;       } else if (wid < 4) {
;         const int sb = wid & 1, tb = wid >> 1;
;         if (sb <= tb) {
;           f32x16 sacc;
; #pragma unroll
;           for (int r = 0; r < 16; ++r) sacc[r] = 0.f;
;           bf16x8 av[8], bv8[8];
; #pragma unroll
;           for (int k16 = 0; k16 < 8; ++k16) {
;             av[k16] = *(const bf16x8*)(kinvL + swz256(sb * 32 + l32, k16 * 2 + hi));
;             bv8[k16] = *(const bf16x8*)(qbL + swz256(tb * 32 + l32, k16 * 2 + hi));
;           }
; #pragma unroll
.Lgs_roles_done:
	s_waitcnt vmcnt(0) lgkmcnt(0)
	s_barrier
	v_lshlrev_b32_e32 v198, 5, v203
	v_add_u32_e32 v198, 0x12000, v198
	v_mov_b32_e32 v112, 0
	v_mov_b32_e32 v113, 0
	v_mov_b32_e32 v114, 0
	v_mov_b32_e32 v115, 0
	ds_write_b128 v198, v[112:115]
	ds_write_b128 v198, v[112:115] offset:16
	v_mov_b32_e32 v0, 0
	v_mov_b32_e32 v1, 0
	v_mov_b32_e32 v2, 0
	v_mov_b32_e32 v3, 0
	v_mov_b32_e32 v4, 0
	v_mov_b32_e32 v5, 0
	v_mov_b32_e32 v6, 0
	v_mov_b32_e32 v7, 0
	v_mov_b32_e32 v8, 0
	v_mov_b32_e32 v9, 0
	v_mov_b32_e32 v10, 0
	v_mov_b32_e32 v11, 0
	v_mov_b32_e32 v12, 0
	v_mov_b32_e32 v13, 0
	v_mov_b32_e32 v14, 0
	v_mov_b32_e32 v15, 0
	s_mov_b32 s54, 0
	s_add_i32 s1, s54, -4
	s_cmp_lt_u32 s54, 4
	s_cselect_b32 s0, s54, s1
	s_movk_i32 s5, 0x1000
	s_cselect_b32 s1, 0x100, s5
	s_lshl_b32 s4, s35, 8
	s_add_u32 s4, s4, 0x8000
	s_lshl_b32 s5, s35, 12
	s_cmp_lt_u32 s54, 4
	s_cselect_b32 s4, s4, s5
	s_lshl_b32 s0, s0, 6
	s_sub_u32 s1, s1, 64
	s_sub_u32 s1, s1, s0
	s_cmp_eq_u32 s55, 0
	s_cselect_b32 s0, s0, s1
	s_add_u32 s0, s4, s0
	s_mul_i32 s1, s0, s34
	s_add_u32 s6, s22, s1
	s_addc_u32 s7, s23, 0
	s_add_u32 s8, s24, s1
	s_addc_u32 s9, s25, 0
	s_mul_i32 s1, s0, 0x1840
	s_add_u32 s10, s26, s1
	s_addc_u32 s11, s27, 0
	s_lshr_b32 s1, s0, 6
	s_lshl_b32 s1, s1, 11
	s_add_u32 s18, s28, s1
	s_addc_u32 s19, s29, 0
	global_load_dwordx4 v[112:115], v166, s[6:7]
	global_load_dwordx4 v[116:119], v166, s[6:7] offset:128
	global_load_dwordx4 v[120:123], v166, s[8:9]
	global_load_dwordx4 v[124:127], v166, s[8:9] offset:128
	global_load_dwordx4 v[128:131], v183, s[10:11]
	global_load_dword v132, v191, s[18:19]
	s_mov_b32 s65, 1
	s_add_i32 s1, s65, -4
	s_cmp_lt_u32 s65, 4
	s_cselect_b32 s0, s65, s1
	s_movk_i32 s5, 0x1000
	s_cselect_b32 s1, 0x100, s5
	s_lshl_b32 s4, s35, 8
	s_add_u32 s4, s4, 0x8000
	s_lshl_b32 s5, s35, 12
	s_cmp_lt_u32 s65, 4
	s_cselect_b32 s4, s4, s5
	s_lshl_b32 s0, s0, 6
	s_sub_u32 s1, s1, 64
	s_sub_u32 s1, s1, s0
	s_cmp_eq_u32 s55, 0
	s_cselect_b32 s0, s0, s1
	s_add_u32 s0, s4, s0
	s_mul_i32 s1, s0, s34
	s_add_u32 s6, s22, s1
	s_addc_u32 s7, s23, 0
	s_add_u32 s8, s24, s1
	s_addc_u32 s9, s25, 0
	s_mul_i32 s1, s0, 0x1840
	s_add_u32 s10, s26, s1
	s_addc_u32 s11, s27, 0
	s_lshr_b32 s1, s0, 6
	s_lshl_b32 s1, s1, 11
	s_add_u32 s18, s28, s1
	s_addc_u32 s19, s29, 0
	global_load_dwordx4 v[96:99], v166, s[6:7]
	global_load_dwordx4 v[100:103], v166, s[6:7] offset:128
	global_load_dwordx4 v[104:107], v166, s[8:9]
	global_load_dwordx4 v[108:111], v166, s[8:9] offset:128
	global_load_dwordx4 v[136:139], v183, s[10:11]
	global_load_dword v133, v191, s[18:19]
	s_mov_b32 s97, 0
	s_mov_b32 s16, 0
.Lgs_pair:
.Lgs0_chunk:
	s_add_i32 s1, s54, -4
	s_cmp_lt_u32 s54, 4
	s_cselect_b32 s0, s54, s1
	s_movk_i32 s5, 0x1000
	s_cselect_b32 s1, 0x100, s5
	s_lshl_b32 s4, s35, 8
	s_add_u32 s4, s4, 0x8000
	s_lshl_b32 s5, s35, 12
	s_cmp_lt_u32 s54, 4
	s_cselect_b32 s4, s4, s5
	s_lshl_b32 s0, s0, 6
	s_sub_u32 s1, s1, 64
	s_sub_u32 s1, s1, s0
	s_cmp_eq_u32 s55, 0
	s_cselect_b32 s0, s0, s1
	s_add_u32 s0, s4, s0
	s_lshl_b32 s1, s0, 11
	s_add_u32 s20, s30, s1
	s_addc_u32 s21, s31, 0
	s_cmp_gt_u32 s54, 3
	s_cselect_b32 s96, 1, s60
	s_add_u32 s0, s97, s16
	s_cmp_eq_u32 s0, 0
	s_cbranch_scc1 .Lgs0_w29
	s_cmp_eq_u32 s0, 16
	s_cbranch_scc1 .Lgs0_w45
	s_waitcnt vmcnt(38)
	s_branch .Lgs0_waited
.Lgs0_w45:
	s_waitcnt vmcnt(22)
	s_branch .Lgs0_waited
.Lgs0_w29:
	s_waitcnt vmcnt(6)
.Lgs0_waited:
	ds_write_b128 v192, v[112:115]
	ds_write_b128 v193, v[116:119]
	ds_write_b128 v192, v[120:123] offset:16384
	ds_write_b128 v193, v[124:127] offset:16384
	ds_write_b128 v196, v[128:131]
	s_cmp_gt_u32 s81, 1
	s_cbranch_scc1 .Lgs0_noeb
	ds_write_b32 v197, v132
.Lgs0_noeb:
	s_waitcnt lgkmcnt(0)
	s_barrier
	s_add_u32 s65, s54, 2
	s_min_u32 s65, s65, 67
	s_cmp_eq_u32 s96, 0
	s_cbranch_scc1 .Lgs0_nochain
	s_cmp_eq_u32 s76, 1
	s_cbranch_scc1 .Lgs0_nochain
	ds_read_b128 v[32:35], v220
	ds_read_b128 v[48:51], v228
	v_xor_b32_e32 v198, 32, v220
	v_xor_b32_e32 v199, 32, v228
	ds_read_b128 v[36:39], v198
	ds_read_b128 v[52:55], v199
	v_xor_b32_e32 v198, 64, v220
	v_xor_b32_e32 v199, 64, v228
	ds_read_b128 v[40:43], v198
	ds_read_b128 v[56:59], v199
	v_xor_b32_e32 v198, 96, v220
	v_xor_b32_e32 v199, 96, v228
	ds_read_b128 v[44:47], v198
	ds_read_b128 v[60:63], v199
	s_add_i32 s1, s65, -4
	s_cmp_lt_u32 s65, 4
	s_cselect_b32 s0, s65, s1
	s_movk_i32 s5, 0x1000
	s_cselect_b32 s1, 0x100, s5
	s_lshl_b32 s4, s35, 8
	s_add_u32 s4, s4, 0x8000
	s_lshl_b32 s5, s35, 12
	s_cmp_lt_u32 s65, 4
	s_cselect_b32 s4, s4, s5
	s_lshl_b32 s0, s0, 6
	s_sub_u32 s1, s1, 64
	s_sub_u32 s1, s1, s0
	s_cmp_eq_u32 s55, 0
	s_cselect_b32 s0, s0, s1
	s_add_u32 s0, s4, s0
	s_mul_i32 s1, s0, s34
	s_add_u32 s6, s22, s1
	s_addc_u32 s7, s23, 0
	s_add_u32 s8, s24, s1
	s_addc_u32 s9, s25, 0
	s_mul_i32 s1, s0, 0x1840
	s_add_u32 s10, s26, s1
	s_addc_u32 s11, s27, 0
	s_lshr_b32 s1, s0, 6
	s_lshl_b32 s1, s1, 11
	s_add_u32 s18, s28, s1
	s_addc_u32 s19, s29, 0
	s_waitcnt lgkmcnt(6)
	v_mfma_f32_32x32x16_bf16 v[16:31], v[32:35], v[48:51], 0
	v_xor_b32_e32 v198, 128, v220
	v_xor_b32_e32 v199, 128, v228
	ds_read_b128 v[32:35], v198
	ds_read_b128 v[48:51], v199
	global_load_dwordx4 v[112:115], v166, s[6:7]
	s_waitcnt lgkmcnt(6)
	v_mfma_f32_32x32x16_bf16 v[16:31], v[36:39], v[52:55], v[16:31]
	v_xor_b32_e32 v198, 160, v220
	v_xor_b32_e32 v199, 160, v228
	ds_read_b128 v[36:39], v198
	ds_read_b128 v[52:55], v199
	global_load_dwordx4 v[116:119], v166, s[6:7] offset:128
	s_waitcnt lgkmcnt(6)
	v_mfma_f32_32x32x16_bf16 v[16:31], v[40:43], v[56:59], v[16:31]
	v_xor_b32_e32 v198, 192, v220
	v_xor_b32_e32 v199, 192, v228
	ds_read_b128 v[40:43], v198
	ds_read_b128 v[56:59], v199
	global_load_dwordx4 v[120:123], v166, s[8:9]
	s_waitcnt lgkmcnt(6)
	v_mfma_f32_32x32x16_bf16 v[16:31], v[44:47], v[60:63], v[16:31]
	v_xor_b32_e32 v198, 224, v220
	v_xor_b32_e32 v199, 224, v228
	ds_read_b128 v[44:47], v198
	ds_read_b128 v[60:63], v199
	global_load_dwordx4 v[124:127], v166, s[8:9] offset:128
	s_waitcnt lgkmcnt(6)
	v_mfma_f32_32x32x16_bf16 v[16:31], v[32:35], v[48:51], v[16:31]
	ds_read_b64_tr_b16 v[64:65], v140 offset:16384
	ds_read_b64_tr_b16 v[66:67], v141 offset:16384
	ds_read_b64_tr_b16 v[80:81], v142 offset:49152
	ds_read_b64_tr_b16 v[82:83], v142 offset:49664
	global_load_dwordx4 v[128:131], v183, s[10:11]
	s_waitcnt lgkmcnt(8)
	v_mfma_f32_32x32x16_bf16 v[16:31], v[36:39], v[52:55], v[16:31]
	ds_read_b64_tr_b16 v[68:69], v140 offset:20480
	ds_read_b64_tr_b16 v[70:71], v141 offset:20480
	ds_read_b64_tr_b16 v[84:85], v142 offset:51200
	ds_read_b64_tr_b16 v[86:87], v142 offset:51712
	global_load_dword v132, v191, s[18:19]
	s_waitcnt lgkmcnt(10)
	v_mfma_f32_32x32x16_bf16 v[16:31], v[40:43], v[56:59], v[16:31]
	ds_read_b64_tr_b16 v[72:73], v140 offset:24576
	ds_read_b64_tr_b16 v[74:75], v141 offset:24576
	ds_read_b64_tr_b16 v[88:89], v142 offset:53248
	ds_read_b64_tr_b16 v[90:91], v142 offset:53760
	s_waitcnt lgkmcnt(12)
	v_mfma_f32_32x32x16_bf16 v[16:31], v[44:47], v[60:63], v[16:31]
	s_branch .Lgs0_supd
; __device__ __forceinline__ u16 f2bf(float x) { return (u16)(cvtpk(x, 0.f) & 0xffffu); }
; __device__ __forceinline__ int crow(int r, int hi) { return (r & 3) + 8 * (r >> 2) + 4 * hi; }
; __device__ __forceinline__ void gla_scan_phase(const Params& p, int j, bool need_ctx, char* smem, int tid, int bid) {
;     ...
;       const int kb = wid >> 1, dvb2 = wid & 1;
;       {
;         bf16x8 av[4], bv4[4];
; #pragma unroll
;         for (int k16 = 0; k16 < 4; ++k16) {
;           av[k16] = *(const bf16x8*)(kendT + swz128(kb * 32 + l32, k16 * 2 + hi));
;           bv4[k16] = *(const bf16x8*)(vT + swz128(dvb2 * 32 + l32, k16 * 2 + hi));
;         }
; #pragma unroll
;         for (int k16 = 0; k16 < 4; ++k16) Sacc = __builtin_amdgcn_mfma_f32_32x32x16_bf16(av[k16], bv4[k16], Sacc, 0, 0, 0);
; #pragma unroll
;         for (int rg = 0; rg < 4; ++rg) {
;           const f32x4 e4 = *(const f32x4*)(ebend + kb * 32 + 8 * rg + 4 * hi);
;           Sacc[rg * 4 + 0] *= e4[0]; Sacc[rg * 4 + 1] *= e4[1]; Sacc[rg * 4 + 2] *= e4[2]; Sacc[rg * 4 + 3] *= e4[3];
;         }
;       }
;       __syncthreads();
;       if (wid >= 4 && need_o) {
; #pragma unroll
;         for (int k16 = 0; k16 < 4; ++k16) {
;           if (k16 < 2 || tbo == 1) {
;             const bf16x8 a = *(const bf16x8*)(scL + swz128(tbo * 32 + l32, k16 * 2 + hi));
;             const bf16x8 bv = *(const bf16x8*)(vT + swz128(dvbo * 32 + l32, k16 * 2 + hi));
;             oacc = __builtin_amdgcn_mfma_f32_32x32x16_bf16(a, bv, oacc, 0, 0, 0);
;           }
;         }
;         if (!is_ctx || need_ctx) {
;           u16* O = dir ? OB : OF;
; #pragma unroll
;           for (int r = 0; r < 16; ++r) {
;             const int pos = c * 64 + tbo * 32 + crow(r, hi);
;             const int tok = dir ? TT - 1 - pos : pos;
;             O[(size_t)(base + tok) * 1024 + h * 256 + dvs * 64 + dvbo * 32 + l32] = f2bf(oacc[r]);
;           }
;         }
;       }
;       {
;         const int dv = dvb2 * 32 + l32;
; #pragma unroll
;         for (int rg = 0; rg < 4; ++rg) {
;           const int k0 = kb * 32 + 8 * rg + 4 * hi;
;           u32x2 w = {cvtpk(Sacc[rg * 4 + 0], Sacc[rg * 4 + 1]), cvtpk(Sacc[rg * 4 + 2], Sacc[rg * 4 + 3])};
;           *(u32x2*)(STL + swz256(dv, k0 >> 3) + (k0 & 7) * 2) = w;
;         }
;       }
.Lgs0_nochain:
	ds_read_b64_tr_b16 v[64:65], v140 offset:16384
	ds_read_b64_tr_b16 v[66:67], v141 offset:16384
	ds_read_b64_tr_b16 v[80:81], v142 offset:49152
	ds_read_b64_tr_b16 v[82:83], v142 offset:49664
	ds_read_b64_tr_b16 v[68:69], v140 offset:20480
	ds_read_b64_tr_b16 v[70:71], v141 offset:20480
	ds_read_b64_tr_b16 v[84:85], v142 offset:51200
	ds_read_b64_tr_b16 v[86:87], v142 offset:51712
	ds_read_b64_tr_b16 v[72:73], v140 offset:24576
	ds_read_b64_tr_b16 v[74:75], v141 offset:24576
	ds_read_b64_tr_b16 v[88:89], v142 offset:53248
	ds_read_b64_tr_b16 v[90:91], v142 offset:53760
	s_add_i32 s1, s65, -4
	s_cmp_lt_u32 s65, 4
	s_cselect_b32 s0, s65, s1
	s_movk_i32 s5, 0x1000
	s_cselect_b32 s1, 0x100, s5
	s_lshl_b32 s4, s35, 8
	s_add_u32 s4, s4, 0x8000
	s_lshl_b32 s5, s35, 12
	s_cmp_lt_u32 s65, 4
	s_cselect_b32 s4, s4, s5
	s_lshl_b32 s0, s0, 6
	s_sub_u32 s1, s1, 64
	s_sub_u32 s1, s1, s0
	s_cmp_eq_u32 s55, 0
	s_cselect_b32 s0, s0, s1
	s_add_u32 s0, s4, s0
	s_mul_i32 s1, s0, s34
	s_add_u32 s6, s22, s1
	s_addc_u32 s7, s23, 0
	s_add_u32 s8, s24, s1
	s_addc_u32 s9, s25, 0
	s_mul_i32 s1, s0, 0x1840
	s_add_u32 s10, s26, s1
	s_addc_u32 s11, s27, 0
	s_lshr_b32 s1, s0, 6
	s_lshl_b32 s1, s1, 11
	s_add_u32 s18, s28, s1
	s_addc_u32 s19, s29, 0
	global_load_dwordx4 v[112:115], v166, s[6:7]
	global_load_dwordx4 v[116:119], v166, s[6:7] offset:128
	global_load_dwordx4 v[120:123], v166, s[8:9]
	global_load_dwordx4 v[124:127], v166, s[8:9] offset:128
	global_load_dwordx4 v[128:131], v183, s[10:11]
	global_load_dword v132, v191, s[18:19]
.Lgs0_supd:
	s_waitcnt lgkmcnt(8)
	v_mfma_f32_32x32x16_bf16 v[0:15], v[64:67], v[80:83], v[0:15]
	ds_read_b64_tr_b16 v[76:77], v140 offset:28672
	ds_read_b64_tr_b16 v[78:79], v141 offset:28672
	ds_read_b64_tr_b16 v[92:93], v142 offset:55296
	ds_read_b64_tr_b16 v[94:95], v142 offset:55808
	s_waitcnt lgkmcnt(8)
	v_mfma_f32_32x32x16_bf16 v[0:15], v[68:71], v[84:87], v[0:15]
	s_waitcnt lgkmcnt(4)
	v_mfma_f32_32x32x16_bf16 v[0:15], v[72:75], v[88:91], v[0:15]
	s_waitcnt lgkmcnt(0)
	v_mfma_f32_32x32x16_bf16 v[0:15], v[76:79], v[92:95], v[0:15]
	ds_read_b128 v[48:51], v252 offset:0
	ds_read_b128 v[52:55], v252 offset:32
	ds_read_b128 v[56:59], v252 offset:64
	ds_read_b128 v[60:63], v252 offset:96
	s_cmp_eq_u32 s96, 0
	s_cbranch_scc1 .Lgs0_noscore
	s_cmp_eq_u32 s76, 0
	s_cbranch_scc0 .Lgs0_noscore
	s_nop 7
	v_and_b32_e32 v16, v204, v16
	v_and_b32_e32 v17, v205, v17
	v_and_b32_e32 v18, v206, v18
	v_and_b32_e32 v19, v207, v19
	v_and_b32_e32 v20, v208, v20
	v_and_b32_e32 v21, v209, v21
	v_and_b32_e32 v22, v210, v22
	v_and_b32_e32 v23, v211, v23
	v_and_b32_e32 v24, v212, v24
	v_and_b32_e32 v25, v213, v25
	v_and_b32_e32 v26, v214, v26
	v_and_b32_e32 v27, v215, v27
	v_and_b32_e32 v28, v216, v28
	v_and_b32_e32 v29, v217, v29
	v_and_b32_e32 v30, v218, v30
	v_and_b32_e32 v31, v219, v31
	v_cvt_pk_bf16_f32 v32, v16, v17
	v_cvt_pk_bf16_f32 v33, v18, v19
	v_cvt_pk_bf16_f32 v34, v20, v21
	v_cvt_pk_bf16_f32 v35, v22, v23
	v_cvt_pk_bf16_f32 v36, v24, v25
	v_cvt_pk_bf16_f32 v37, v26, v27
	v_cvt_pk_bf16_f32 v38, v28, v29
	v_cvt_pk_bf16_f32 v39, v30, v31
	v_xor_b32_e32 v198, 16, v249
	v_xor_b32_e32 v199, 32, v249
	v_xor_b32_e32 v200, 48, v249
	ds_write_b64 v249, v[32:33]
	ds_write_b64 v198, v[34:35]
	ds_write_b64 v199, v[36:37]
	ds_write_b64 v200, v[38:39]
.Lgs0_noscore:
	s_nop 7
	s_nop 3
	s_waitcnt lgkmcnt(0)
	v_mul_f32_e32 v0, v0, v48
	v_mul_f32_e32 v1, v1, v49
	v_mul_f32_e32 v2, v2, v50
	v_mul_f32_e32 v3, v3, v51
	v_mul_f32_e32 v4, v4, v52
	v_mul_f32_e32 v5, v5, v53
	v_mul_f32_e32 v6, v6, v54
	v_mul_f32_e32 v7, v7, v55
	v_mul_f32_e32 v8, v8, v56
	v_mul_f32_e32 v9, v9, v57
	v_mul_f32_e32 v10, v10, v58
	v_mul_f32_e32 v11, v11, v59
	v_mul_f32_e32 v12, v12, v60
	v_mul_f32_e32 v13, v13, v61
	v_mul_f32_e32 v14, v14, v62
	v_mul_f32_e32 v15, v15, v63
	s_barrier
	s_mov_b32 s16, s97
	s_mov_b32 s97, 0
	s_cmp_eq_u32 s96, 0
	s_cbranch_scc1 .Lgs0_state
	s_cmp_eq_u32 s76, 2
	s_cbranch_scc0 .Lgs0_state
	v_xor_b32_e32 v198, 32, v249
	ds_read_b128 v[32:35], v249
	ds_read_b128 v[36:39], v198
	s_cmp_eq_u32 s77, 0
	s_cbranch_scc1 .Lgs0_ohalf
	v_xor_b32_e32 v199, 64, v249
	v_xor_b32_e32 v200, 96, v249
	ds_read_b128 v[40:43], v199
	ds_read_b128 v[44:47], v200
	s_waitcnt lgkmcnt(2)
	v_mfma_f32_32x32x16_bf16 v[16:31], v[32:35], v[80:83], v[16:31]
	v_mfma_f32_32x32x16_bf16 v[16:31], v[36:39], v[84:87], v[16:31]
	s_waitcnt lgkmcnt(0)
	v_mfma_f32_32x32x16_bf16 v[16:31], v[40:43], v[88:91], v[16:31]
	v_mfma_f32_32x32x16_bf16 v[16:31], v[44:47], v[92:95], v[16:31]
	s_branch .Lgs0_ostore
.Lgs0_ohalf:
	s_waitcnt lgkmcnt(0)
	v_mfma_f32_32x32x16_bf16 v[16:31], v[32:35], v[80:83], v[16:31]
	v_mfma_f32_32x32x16_bf16 v[16:31], v[36:39], v[84:87], v[16:31]
.Lgs0_ostore:
	v_cvt_pk_bf16_f32 v48, v0, v1
	v_cvt_pk_bf16_f32 v49, v2, v3
	v_cvt_pk_bf16_f32 v50, v4, v5
	v_cvt_pk_bf16_f32 v51, v6, v7
	v_cvt_pk_bf16_f32 v52, v8, v9
	v_cvt_pk_bf16_f32 v53, v10, v11
	v_cvt_pk_bf16_f32 v54, v12, v13
	v_cvt_pk_bf16_f32 v55, v14, v15
	v_xor_b32_e32 v198, 16, v250
	v_xor_b32_e32 v199, 32, v250
	v_xor_b32_e32 v200, 48, v250
	ds_write_b64 v250, v[48:49]
	ds_write_b64 v198, v[50:51]
	ds_write_b64 v199, v[52:53]
	ds_write_b64 v200, v[54:55]
	s_nop 3
	v_cvt_pk_bf16_f32 v198, v16, v201
	global_store_short v204, v198, s[20:21]
	v_cvt_pk_bf16_f32 v199, v17, v201
	global_store_short v205, v199, s[20:21]
	v_cvt_pk_bf16_f32 v200, v18, v201
	global_store_short v206, v200, s[20:21]
	v_cvt_pk_bf16_f32 v153, v19, v201
	global_store_short v207, v153, s[20:21]
	v_cvt_pk_bf16_f32 v198, v20, v201
	global_store_short v208, v198, s[20:21]
	v_cvt_pk_bf16_f32 v199, v21, v201
	global_store_short v209, v199, s[20:21]
	v_cvt_pk_bf16_f32 v200, v22, v201
	global_store_short v210, v200, s[20:21]
	v_cvt_pk_bf16_f32 v153, v23, v201
	global_store_short v211, v153, s[20:21]
	v_cvt_pk_bf16_f32 v198, v24, v201
	global_store_short v212, v198, s[20:21]
	v_cvt_pk_bf16_f32 v199, v25, v201
	global_store_short v213, v199, s[20:21]
	v_cvt_pk_bf16_f32 v200, v26, v201
	global_store_short v214, v200, s[20:21]
	v_cvt_pk_bf16_f32 v153, v27, v201
	global_store_short v215, v153, s[20:21]
	v_cvt_pk_bf16_f32 v198, v28, v201
	global_store_short v216, v198, s[20:21]
	v_cvt_pk_bf16_f32 v199, v29, v201
	global_store_short v217, v199, s[20:21]
	v_cvt_pk_bf16_f32 v200, v30, v201
	global_store_short v218, v200, s[20:21]
	v_cvt_pk_bf16_f32 v153, v31, v201
	global_store_short v219, v153, s[20:21]
	s_mov_b32 s97, 16
	s_branch .Lgs0_next
.Lgs0_state:
	v_cvt_pk_bf16_f32 v48, v0, v1
	v_cvt_pk_bf16_f32 v49, v2, v3
	v_cvt_pk_bf16_f32 v50, v4, v5
	v_cvt_pk_bf16_f32 v51, v6, v7
	v_cvt_pk_bf16_f32 v52, v8, v9
	v_cvt_pk_bf16_f32 v53, v10, v11
	v_cvt_pk_bf16_f32 v54, v12, v13
	v_cvt_pk_bf16_f32 v55, v14, v15
	v_xor_b32_e32 v198, 16, v250
	v_xor_b32_e32 v199, 32, v250
	v_xor_b32_e32 v200, 48, v250
	ds_write_b64 v250, v[48:49]
	ds_write_b64 v198, v[50:51]
	ds_write_b64 v199, v[52:53]
	ds_write_b64 v200, v[54:55]

; __device__ __forceinline__ void gla_scan_phase(const Params& p, int j, bool need_ctx, char* smem, int tid, int bid) {
;     ...
;     for (int ci = 0; ci < 68; ++ci) {
;       asm volatile("" : "+v"(tid));
;       const int lane = tid & 63, wid = tid >> 6, l32 = lane & 31, hi = lane >> 5;
;       const int tbg = wid >> 2, kd = (wid & 3) * 32 + l32;
;       const int dvc = tid & 63, tg = tid >> 6;
;       const bool is_ctx = ci < 4; const int c = is_ctx ? ci : ci - 4; const int TT = is_ctx ? CTXL : SEQL;
;       const int base = is_ctx ? ML + b * CTXL : b * SEQL;
;       char* vT = vT0 + (ci & 1) * 40960;
;       {
.Lgs1_chunk:
	s_add_i32 s1, s54, -4
	s_cmp_lt_u32 s54, 4
	s_cselect_b32 s0, s54, s1
	s_movk_i32 s5, 0x1000
	s_cselect_b32 s1, 0x100, s5
	s_lshl_b32 s4, s35, 8
	s_add_u32 s4, s4, 0x8000
	s_lshl_b32 s5, s35, 12
	s_cmp_lt_u32 s54, 4
	s_cselect_b32 s4, s4, s5
	s_lshl_b32 s0, s0, 6
	s_sub_u32 s1, s1, 64
	s_sub_u32 s1, s1, s0
	s_cmp_eq_u32 s55, 0
	s_cselect_b32 s0, s0, s1
	s_add_u32 s0, s4, s0
	s_lshl_b32 s1, s0, 11
	s_add_u32 s20, s30, s1
	s_addc_u32 s21, s31, 0
	s_cmp_gt_u32 s54, 3
	s_cselect_b32 s96, 1, s60
	s_add_u32 s0, s97, s16
	s_cmp_eq_u32 s0, 0
	s_cbranch_scc1 .Lgs1_w29
	s_cmp_eq_u32 s0, 16
	s_cbranch_scc1 .Lgs1_w45
	s_waitcnt vmcnt(38)
	s_branch .Lgs1_waited

; __device__ __forceinline__ void gla_scan_phase(const Params& p, int j, bool need_ctx, char* smem, int tid, int bid) {
;     ...
;       {
;         if (tid < 128) ebend[tid] = ebv;
;         const int r = tid >> 3, c0 = tid & 7;
;         *(u32x4*)(qbL + swz256(r, c0)) = qx[0]; *(u32x4*)(qbL + swz256(r, c0 + 8)) = qx[1];
;         *(u32x4*)(kinvL + swz256(r, c0)) = kx[0]; *(u32x4*)(kinvL + swz256(r, c0 + 8)) = kx[1];
;         const int kdt = tid & 127, tgk = tid >> 7;
;         u32x4 w0 = {kt[0] | (kt[1] << 16), kt[2] | (kt[3] << 16), kt[4] | (kt[5] << 16), kt[6] | (kt[7] << 16)};
;         u32x4 w1 = {kt[8] | (kt[9] << 16), kt[10] | (kt[11] << 16), kt[12] | (kt[13] << 16), kt[14] | (kt[15] << 16)};
;         *(u32x4*)(kendT + swz128(kdt, tgk)) = w0;
;         *(u32x4*)(kendT + swz128(kdt, tgk + 4)) = w1;
;         u32x4 wv = {vv[0] | (vv[1] << 16), vv[2] | (vv[3] << 16), vv[4] | (vv[5] << 16), vv[6] | (vv[7] << 16)};
;         *(u32x4*)(vT + swz128(dvc, tg)) = wv;
;       }
;       __builtin_amdgcn_sched_barrier(0);
;       if (ci + 1 < 68) GLA_PREFETCH(ci + 1);
;       __builtin_amdgcn_sched_barrier(0);
;       __syncthreads();
;       f32x16 oacc;
; #pragma unroll
;       for (int r = 0; r < 16; ++r) oacc[r] = 0.f;
;       const int tbo = (wid - 4) >> 1, dvbo = (wid - 4) & 1;
;       const bool need_o = !is_ctx || need_ctx;
;       if (!need_o) {
;       } else if (wid < 4) {
;         const int sb = wid & 1, tb = wid >> 1;
;         if (sb <= tb) {
;           f32x16 sacc;
; #pragma unroll
;           for (int r = 0; r < 16; ++r) sacc[r] = 0.f;
;           bf16x8 av[8], bv8[8];
; #pragma unroll
;           for (int k16 = 0; k16 < 8; ++k16) {
;             av[k16] = *(const bf16x8*)(kinvL + swz256(sb * 32 + l32, k16 * 2 + hi));
;             bv8[k16] = *(const bf16x8*)(qbL + swz256(tb * 32 + l32, k16 * 2 + hi));
;           }
; #pragma unroll
;           for (int k16 = 0; k16 < 8; ++k16) sacc = __builtin_amdgcn_mfma_f32_32x32x16_bf16(av[k16], bv8[k16], sacc, 0, 0, 0);
;           const int t = tb * 32 + l32;
; #pragma unroll
;           for (int rg = 0; rg < 4; ++rg) {
;             const int s0 = sb * 32 + 8 * rg + 4 * hi;
;             const float v0 = (s0 + 0 <= t) ? sacc[rg * 4 + 0] : 0.f, v1 = (s0 + 1 <= t) ? sacc[rg * 4 + 1] : 0.f;
;             const float v2 = (s0 + 2 <= t) ? sacc[rg * 4 + 2] : 0.f, v3 = (s0 + 3 <= t) ? sacc[rg * 4 + 3] : 0.f;
.Lgs1_waited:
	ds_write_b128 v192, v[96:99]
	ds_write_b128 v193, v[100:103]
	ds_write_b128 v192, v[104:107] offset:16384
	ds_write_b128 v193, v[108:111] offset:16384
	ds_write_b128 v196, v[136:139]
	s_cmp_gt_u32 s81, 1
	s_cbranch_scc1 .Lgs1_noeb
	ds_write_b32 v197, v133
.Lgs1_noeb:
	s_waitcnt lgkmcnt(0)
	s_barrier
	s_add_u32 s65, s54, 2
	s_min_u32 s65, s65, 67
	s_cmp_eq_u32 s96, 0
	s_cbranch_scc1 .Lgs1_nochain
	s_cmp_eq_u32 s76, 1
	s_cbranch_scc1 .Lgs1_nochain
	ds_read_b128 v[32:35], v220
	ds_read_b128 v[48:51], v228
	v_xor_b32_e32 v198, 32, v220
	v_xor_b32_e32 v199, 32, v228
	ds_read_b128 v[36:39], v198
	ds_read_b128 v[52:55], v199
	v_xor_b32_e32 v198, 64, v220
	v_xor_b32_e32 v199, 64, v228
	ds_read_b128 v[40:43], v198
	ds_read_b128 v[56:59], v199
	v_xor_b32_e32 v198, 96, v220
	v_xor_b32_e32 v199, 96, v228
	ds_read_b128 v[44:47], v198
	ds_read_b128 v[60:63], v199
	s_add_i32 s1, s65, -4
	s_cmp_lt_u32 s65, 4
	s_cselect_b32 s0, s65, s1
	s_movk_i32 s5, 0x1000
	s_cselect_b32 s1, 0x100, s5
	s_lshl_b32 s4, s35, 8
	s_add_u32 s4, s4, 0x8000
	s_lshl_b32 s5, s35, 12
	s_cmp_lt_u32 s65, 4
	s_cselect_b32 s4, s4, s5
	s_lshl_b32 s0, s0, 6
	s_sub_u32 s1, s1, 64
	s_sub_u32 s1, s1, s0
	s_cmp_eq_u32 s55, 0
	s_cselect_b32 s0, s0, s1
	s_add_u32 s0, s4, s0
	s_mul_i32 s1, s0, s34
	s_add_u32 s6, s22, s1
	s_addc_u32 s7, s23, 0
	s_add_u32 s8, s24, s1
	s_addc_u32 s9, s25, 0
	s_mul_i32 s1, s0, 0x1840
	s_add_u32 s10, s26, s1
	s_addc_u32 s11, s27, 0
	s_lshr_b32 s1, s0, 6
	s_lshl_b32 s1, s1, 11
	s_add_u32 s18, s28, s1
	s_addc_u32 s19, s29, 0
	s_waitcnt lgkmcnt(6)
	v_mfma_f32_32x32x16_bf16 v[16:31], v[32:35], v[48:51], 0
	v_xor_b32_e32 v198, 128, v220
	v_xor_b32_e32 v199, 128, v228
	ds_read_b128 v[32:35], v198
	ds_read_b128 v[48:51], v199
	global_load_dwordx4 v[96:99], v166, s[6:7]
	s_waitcnt lgkmcnt(6)
	v_mfma_f32_32x32x16_bf16 v[16:31], v[36:39], v[52:55], v[16:31]
	v_xor_b32_e32 v198, 160, v220
	v_xor_b32_e32 v199, 160, v228
	ds_read_b128 v[36:39], v198
	ds_read_b128 v[52:55], v199
	global_load_dwordx4 v[100:103], v166, s[6:7] offset:128
	s_waitcnt lgkmcnt(6)
	v_mfma_f32_32x32x16_bf16 v[16:31], v[40:43], v[56:59], v[16:31]
	v_xor_b32_e32 v198, 192, v220
	v_xor_b32_e32 v199, 192, v228
	ds_read_b128 v[40:43], v198
	ds_read_b128 v[56:59], v199
	global_load_dwordx4 v[104:107], v166, s[8:9]
	s_waitcnt lgkmcnt(6)
	v_mfma_f32_32x32x16_bf16 v[16:31], v[44:47], v[60:63], v[16:31]
	v_xor_b32_e32 v198, 224, v220
	v_xor_b32_e32 v199, 224, v228
	ds_read_b128 v[44:47], v198
	ds_read_b128 v[60:63], v199
	global_load_dwordx4 v[108:111], v166, s[8:9] offset:128
	s_waitcnt lgkmcnt(6)
	v_mfma_f32_32x32x16_bf16 v[16:31], v[32:35], v[48:51], v[16:31]
	ds_read_b64_tr_b16 v[64:65], v140 offset:16384
	ds_read_b64_tr_b16 v[66:67], v141 offset:16384
	ds_read_b64_tr_b16 v[80:81], v142 offset:49152
	ds_read_b64_tr_b16 v[82:83], v142 offset:49664
	global_load_dwordx4 v[136:139], v183, s[10:11]
	s_waitcnt lgkmcnt(8)
	v_mfma_f32_32x32x16_bf16 v[16:31], v[36:39], v[52:55], v[16:31]
	ds_read_b64_tr_b16 v[68:69], v140 offset:20480
	ds_read_b64_tr_b16 v[70:71], v141 offset:20480
	ds_read_b64_tr_b16 v[84:85], v142 offset:51200
	ds_read_b64_tr_b16 v[86:87], v142 offset:51712
	global_load_dword v133, v191, s[18:19]
	s_waitcnt lgkmcnt(10)
	v_mfma_f32_32x32x16_bf16 v[16:31], v[40:43], v[56:59], v[16:31]
	ds_read_b64_tr_b16 v[72:73], v140 offset:24576
	ds_read_b64_tr_b16 v[74:75], v141 offset:24576
	ds_read_b64_tr_b16 v[88:89], v142 offset:53248
	ds_read_b64_tr_b16 v[90:91], v142 offset:53760
	s_waitcnt lgkmcnt(12)
	v_mfma_f32_32x32x16_bf16 v[16:31], v[44:47], v[60:63], v[16:31]
	s_branch .Lgs1_supd
.Lgs1_nochain:
	ds_read_b64_tr_b16 v[64:65], v140 offset:16384
	ds_read_b64_tr_b16 v[66:67], v141 offset:16384
	ds_read_b64_tr_b16 v[80:81], v142 offset:49152
	ds_read_b64_tr_b16 v[82:83], v142 offset:49664
	ds_read_b64_tr_b16 v[68:69], v140 offset:20480
	ds_read_b64_tr_b16 v[70:71], v141 offset:20480
	ds_read_b64_tr_b16 v[84:85], v142 offset:51200
	ds_read_b64_tr_b16 v[86:87], v142 offset:51712
	ds_read_b64_tr_b16 v[72:73], v140 offset:24576
	ds_read_b64_tr_b16 v[74:75], v141 offset:24576
	ds_read_b64_tr_b16 v[88:89], v142 offset:53248
	ds_read_b64_tr_b16 v[90:91], v142 offset:53760
	s_add_i32 s1, s65, -4
	s_cmp_lt_u32 s65, 4
	s_cselect_b32 s0, s65, s1
	s_movk_i32 s5, 0x1000
	s_cselect_b32 s1, 0x100, s5
	s_lshl_b32 s4, s35, 8
	s_add_u32 s4, s4, 0x8000
	s_lshl_b32 s5, s35, 12
	s_cmp_lt_u32 s65, 4
	s_cselect_b32 s4, s4, s5
	s_lshl_b32 s0, s0, 6
	s_sub_u32 s1, s1, 64
	s_sub_u32 s1, s1, s0
	s_cmp_eq_u32 s55, 0
	s_cselect_b32 s0, s0, s1
	s_add_u32 s0, s4, s0
	s_mul_i32 s1, s0, s34
	s_add_u32 s6, s22, s1
	s_addc_u32 s7, s23, 0
	s_add_u32 s8, s24, s1
	s_addc_u32 s9, s25, 0
	s_mul_i32 s1, s0, 0x1840
	s_add_u32 s10, s26, s1
	s_addc_u32 s11, s27, 0
	s_lshr_b32 s1, s0, 6
	s_lshl_b32 s1, s1, 11
	s_add_u32 s18, s28, s1
	s_addc_u32 s19, s29, 0
	global_load_dwordx4 v[96:99], v166, s[6:7]
	global_load_dwordx4 v[100:103], v166, s[6:7] offset:128
	global_load_dwordx4 v[104:107], v166, s[8:9]
	global_load_dwordx4 v[108:111], v166, s[8:9] offset:128
	global_load_dwordx4 v[136:139], v183, s[10:11]
	global_load_dword v133, v191, s[18:19]
